# S4: rstd of the quad's 512 rows computed once at stage entry into an LDS table; unit epilogues read it instead of reloading and re-reducing 16 row partials per row
# speedup vs baseline: 1.0002x; 1.0002x over previous
.LBB0_983:
	s_or_b64 exec, exec, s[6:7]
	v_readlane_b32 s98, v246, 2
	v_readlane_b32 s99, v246, 3
	s_ashr_i32 s100, s86, 1
	s_and_b32 s100, s100, -2
	s_lshl_b32 s100, s100, 14
	s_add_u32 s98, s98, s100
	s_addc_u32 s99, s99, 0
	s_add_u32 s98, s98, 0x1bb00000
	s_addc_u32 s99, s99, 0
	v_lshlrev_b32_e32 v130, 6, v0
	global_load_dwordx4 v[114:117], v130, s[98:99]
	global_load_dwordx4 v[118:121], v130, s[98:99] offset:16
	global_load_dwordx4 v[122:125], v130, s[98:99] offset:32
	global_load_dwordx4 v[126:129], v130, s[98:99] offset:48
	v_readlane_b32 s0, v246, 2
	v_readlane_b32 s1, v246, 3
	s_add_u32 s48, s0, 0xb600000
	s_addc_u32 s49, s1, 0
	v_lshrrev_b32_e32 v3, 1, v0
	v_lshrrev_b32_e32 v4, 5, v0
	s_add_u32 s50, s0, 0x1300000
	v_lshlrev_b32_e32 v1, 4, v0
	v_and_b32_e32 v2, 32, v0
	v_and_b32_e32 v3, 24, v3
	v_and_b32_e32 v4, 4, v4
	v_bfe_u32 v5, v0, 2, 2
	s_addc_u32 s51, s1, 0
	s_ashr_i32 s2, s86, 1
	v_bfe_u32 v12, v0, 2, 4
	v_bitop3_b32 v10, v1, v2, 48 bitop3:0x6c
	v_and_b32_e32 v11, 64, v0
	v_or3_b32 v3, v4, v5, v3
	v_lshrrev_b32_e32 v4, 3, v0
	v_or_b32_e32 v13, 0x2000, v1
	v_readfirstlane_b32 s0, v0
	v_or_b32_e32 v2, v10, v11
	v_and_or_b32 v5, v4, 48, v12
	v_and_or_b32 v4, v4, 32, v3
	v_lshrrev_b32_e32 v1, 7, v13
	s_movk_i32 s1, 0x70
	s_or_b32 s6, s2, 1
	s_and_b32 s52, s86, 3
	s_lshr_b32 s3, s0, 6
	v_lshl_or_b32 v184, v4, 11, v2
	v_and_or_b32 v4, v1, s1, v12
	s_movk_i32 s1, 0x60
	s_ashr_i32 s7, s6, 31
	v_and_or_b32 v1, v1, s1, v3
	s_lshr_b32 s1, s0, 8
	s_lshl_b32 s53, s3, 10
	s_lshl_b64 s[4:5], s[6:7], 19
	s_lshl_b32 s7, s52, 19
	s_add_u32 s10, s50, s7
	s_addc_u32 s11, s51, 0
	s_add_i32 s54, s53, 0
	s_add_i32 m0, s54, 0x10000
	v_lshl_or_b32 v188, v1, 11, v2
	global_load_lds_dwordx4 v184, s[10:11]
	s_add_i32 m0, s54, 0x12000
	s_add_u32 s8, s10, 0x40000
	global_load_lds_dwordx4 v188, s[10:11]
	s_addc_u32 s9, s11, 0
	s_add_i32 m0, s54, 0x14000
	v_lshl_or_b32 v182, v5, 11, v2
	global_load_lds_dwordx4 v184, s[8:9]
	s_add_i32 m0, s54, 0x16000
	v_lshl_or_b32 v186, v4, 11, v2
	global_load_lds_dwordx4 v188, s[8:9]
	s_add_u32 s8, s48, s4
	s_addc_u32 s9, s49, s5
	s_add_i32 s55, s54, 0x2000
	s_mov_b32 m0, s54
	s_add_u32 s4, s8, 0x40000
	global_load_lds_dwordx4 v182, s[8:9]
	s_mov_b32 m0, s55
	s_addc_u32 s5, s9, 0
	s_add_i32 s56, s54, 0x4000
	global_load_lds_dwordx4 v186, s[8:9]
	s_mov_b32 m0, s56
	s_add_i32 s57, s54, 0x6000
	global_load_lds_dwordx4 v182, s[4:5]
	s_mov_b32 m0, s57
	v_mov_b32_e32 v185, 0
	global_load_lds_dwordx4 v186, s[4:5]
	v_readlane_b32 s4, v246, 0
	v_readlane_b32 s5, v246, 1
	s_load_dwordx8 s[12:19], s[4:5], 0x10
	s_load_dwordx2 s[20:21], s[4:5], 0xa0
	v_mov_b32_e32 v189, v185
	v_mov_b32_e32 v183, v185
	v_mov_b32_e32 v187, v185
	s_cmp_eq_u32 s1, 1
	s_mov_b32 s23, 0
	v_lshl_add_u64 v[8:9], s[10:11], 0, v[184:185]
	v_lshl_add_u64 v[6:7], s[10:11], 0, v[188:189]
	v_lshl_add_u64 v[2:3], s[8:9], 0, v[182:183]
	s_cselect_b64 s[24:25], -1, 0
	s_cmp_lg_u32 s1, 1
	v_lshl_add_u64 v[4:5], s[8:9], 0, v[186:187]
	s_cbranch_scc1 .LBB0_985
	s_barrier
.LBB0_985:
	v_readlane_b32 s34, v246, 2
	v_readlane_b32 s35, v246, 3
	s_add_u32 s26, s34, 0xf800000
	s_mov_b64 s[28:29], 0x80
	s_addc_u32 s27, s35, 0
	s_and_b32 s4, s3, 3
	s_add_i32 m0, s54, 0x18000
	v_lshl_add_u64 v[8:9], v[8:9], 0, s[28:29]
	s_lshl_b32 s58, s33, 1
	s_lshl_b32 s5, s1, 13
	s_lshl_b32 s7, s4, 12
	s_and_b32 s59, s2, -2
	s_waitcnt vmcnt(2)
	s_barrier
	global_load_lds_dwordx4 v[8:9], off
	v_lshl_add_u64 v[6:7], v[6:7], 0, s[28:29]
	s_add_i32 m0, s54, 0x1a000
	s_add_i32 s60, s54, 0x8000
	s_add_i32 s61, s54, 0xa000
	global_load_lds_dwordx4 v[6:7], off
	v_lshl_add_u64 v[2:3], v[2:3], 0, s[28:29]
	s_mov_b32 m0, s60
	s_add_u32 s2, s10, 0x40080
	global_load_lds_dwordx4 v[2:3], off
	v_lshl_add_u64 v[2:3], v[4:5], 0, s[28:29]
	s_mov_b32 m0, s61
	s_addc_u32 s3, s11, 0
	global_load_lds_dwordx4 v[2:3], off
	s_add_i32 m0, s54, 0x1c000
	v_lshl_add_u64 v[2:3], s[2:3], 0, v[184:185]
	global_load_lds_dwordx4 v[2:3], off
	v_lshl_add_u64 v[2:3], s[2:3], 0, v[188:189]
	s_add_i32 m0, s54, 0x1e000
	v_and_b32_e32 v179, 15, v0
	global_load_lds_dwordx4 v[2:3], off
	v_bfe_u32 v2, v0, 4, 2
	v_lshl_or_b32 v212, s1, 6, v179
	v_lshlrev_b32_e32 v3, 3, v2
	v_lshlrev_b32_e32 v2, 4, v2
	v_lshlrev_b32_e32 v6, 6, v0
	s_movk_i32 s1, 0x3c0
	s_cmpk_lt_u32 s0, 0x100
	v_and_or_b32 v6, v6, s1, v2
	s_cselect_b64 s[30:31], -1, 0
	s_and_b32 s0, s0, 0xffffff00
	s_lshl_b32 s1, s4, 6
	v_lshl_or_b32 v214, s4, 5, v3
	s_or_b32 s0, s1, s0
	v_mov_b32_e32 v3, v185
	v_lshl_or_b32 v4, v179, 6, v2
	v_or3_b32 v215, s0, v2, v179
	v_lshl_add_u64 v[2:3], s[34:35], 0, v[2:3]
	s_mov_b64 s[0:1], 0x1bb00000
	v_lshl_add_u64 v[190:191], v[2:3], 0, s[0:1]
	v_lshlrev_b32_e32 v2, 8, v0
	v_and_b32_e32 v2, 0x18000, v2
	v_lshlrev_b32_e32 v3, 11, v12
	v_or3_b32 v2, v10, v2, v3
	v_add_u32_e32 v192, v2, v11
	v_lshlrev_b32_e32 v2, 4, v13
	v_and_b32_e32 v2, 0x38000, v2
	v_and_b32_e32 v5, 32, v180
	s_waitcnt vmcnt(6)
	s_add_u32 s34, s34, 0x3e40
	v_or3_b32 v2, v10, v2, v3
	v_bitop3_b32 v4, v4, s5, v5 bitop3:0xde
	v_bitop3_b32 v213, s7, v6, v5 bitop3:0xf6
	s_addc_u32 s35, s35, 0
	v_add_u32_e32 v194, v2, v11
	s_add_i32 s62, 0, 0x10000
	s_add_i32 s63, 0, 0x14000
	v_mbcnt_lo_u32_b32 v2, -1, 0
	v_lshrrev_b32_e32 v1, 4, v0
	v_add_u32_e32 v216, 0x200, v215
	v_add_u32_e32 v217, 0x400, v215
	v_add_u32_e32 v218, 0x600, v215
	v_mov_b32_e32 v193, v185
	v_mov_b32_e32 v195, v185
	v_add_u32_e32 v219, s62, v213
	v_add_u32_e32 v220, s63, v213
	v_add_u32_e32 v221, 0, v4
	s_movk_i32 s64, 0x80
	s_movk_i32 s65, 0x1550
	s_movk_i32 s66, 0x154f
	s_movk_i32 s67, 0xfb10
	v_mbcnt_hi_u32_b32 v181, -1, v2
	v_mov_b32_e32 v222, 0x358637bd
	s_movk_i32 s68, 0x1600
	s_mov_b32 s69, 0x34a0000
	s_add_i32 s70, 0, 0x201ac
	s_mov_b32 s0, s52
	s_mov_b32 s72, 0
	s_waitcnt vmcnt(0)
	v_add_f32_e32 v114, v114, v115
	v_add_f32_e32 v116, v116, v117
	v_add_f32_e32 v118, v118, v119
	v_add_f32_e32 v120, v120, v121
	v_add_f32_e32 v122, v122, v123
	v_add_f32_e32 v124, v124, v125
	v_add_f32_e32 v126, v126, v127
	v_add_f32_e32 v128, v128, v129
	v_add_f32_e32 v114, v114, v116
	v_add_f32_e32 v118, v118, v120
	v_add_f32_e32 v122, v122, v124
	v_add_f32_e32 v126, v126, v128
	v_add_f32_e32 v114, v114, v118
	v_add_f32_e32 v122, v122, v126
	v_add_f32_e32 v114, v114, v122
	v_fmamk_f32 v114, v114, 0x3a800000, v222
	v_rsq_f32_e32 v114, v114
	v_mov_b32_e32 v131, 0x21000
	v_lshl_add_u32 v131, v0, 2, v131
	ds_write_b32 v131, v114
	s_waitcnt lgkmcnt(0)
	s_barrier
	s_branch .LBB0_988

.LBB0_994:
	s_sub_i32 s99, s6, s59
	s_lshl_b32 s99, s99, 10
	s_add_i32 s99, s99, 0x21000
	s_sub_i32 s1, s58, s6
	s_mul_i32 s1, s1, 22
	s_add_i32 s1, s0, s1
	s_add_i32 s1, s1, 22
	s_ashr_i32 s1, s1, 2
	s_and_b32 s37, s1, 1
	s_lshl_b32 s2, s37, 2
	v_lshl_add_u32 v210, s6, 8, v212
	s_add_i32 s2, s2, 0
	s_add_i32 s2, s2, 0x201a0
	v_or_b32_e32 v208, 16, v210
	v_mov_b32_e32 v66, s2
	v_ashrrev_i32_e32 v211, 31, v210
	v_ashrrev_i32_e32 v209, 31, v208
	ds_read_b32 v146, v66
	v_or_b32_e32 v206, 32, v210
	v_or_b32_e32 v204, 48, v210
	v_ashrrev_i32_e32 v207, 31, v206
	v_ashrrev_i32_e32 v205, 31, v204
	v_add_u32_e32 v202, 0x80, v210
	v_add_u32_e32 v200, 0x90, v210
	v_ashrrev_i32_e32 v203, 31, v202
	v_ashrrev_i32_e32 v201, 31, v200
	v_add_u32_e32 v198, 0xa0, v210
	v_add_u32_e32 v196, 0xb0, v210
	v_ashrrev_i32_e32 v199, 31, v198
	v_ashrrev_i32_e32 v197, 31, v196
	v_lshl_add_u32 v247, v212, 2, s99
	ds_read_b32 v174, v247
	ds_read_b32 v170, v247 offset:64
	ds_read_b32 v166, v247 offset:128
	ds_read_b32 v162, v247 offset:192
	ds_read_b32 v106, v247 offset:512
	ds_read_b32 v86, v247 offset:576
	ds_read_b32 v70, v247 offset:640
	ds_read_b32 v66, v247 offset:704
	s_waitcnt lgkmcnt(0)
	v_readfirstlane_b32 s2, v146
	v_cmp_lt_i32_e32 vcc, s66, v146
	v_mov_b32_e32 v153, 0
	v_cmp_gt_i32_e64 s[6:7], s65, v146
	s_and_b64 vcc, exec, vcc
	v_mov_b32_e32 v152, 0
	v_mov_b32_e32 v151, 0
	v_mov_b32_e32 v150, 0
	v_mov_b32_e32 v157, 0
	v_mov_b32_e32 v156, 0
	v_mov_b32_e32 v155, 0
	v_mov_b32_e32 v154, 0
	v_mov_b32_e32 v149, 0
	v_mov_b32_e32 v148, 0
	v_mov_b32_e32 v147, 0
	v_mov_b32_e32 v146, 0
	v_mov_b32_e32 v161, 0
	v_mov_b32_e32 v160, 0
	v_mov_b32_e32 v159, 0
	v_mov_b32_e32 v158, 0
	s_bitcmp1_b32 s30, 0
	s_cbranch_scc0 .Lae4_skip
	s_barrier

.Ls4_nocp:
.LBB0_1012:
	v_lshl_or_b32 v224, s0, 7, v214
	v_and_b32_e32 v197, 64, v181
	v_add_u32_e32 v197, 64, v197
	s_nop 0
	v_ashrrev_i32_e32 v225, 31, v224
	s_waitcnt lgkmcnt(0)
	s_waitcnt lgkmcnt(0)
	v_mov_b32_e32 v176, v174
	s_nop 0
	v_pk_mul_f32 v[142:143], v[142:143], v[176:177] op_sel_hi:[1,0]
	s_nop 0
	v_mul_f32_e32 v175, 0xbfb8aa3b, v142
	v_mul_f32_e32 v177, 0xbfb8aa3b, v143
	v_exp_f32_e32 v175, v175
	v_exp_f32_e32 v177, v177
	v_add_f32_e32 v175, 1.0, v175
	v_add_f32_e32 v177, 1.0, v177
	v_rcp_f32_e32 v226, v175
	v_rcp_f32_e32 v227, v177
	v_pk_mul_f32 v[144:145], v[144:145], v[176:177] op_sel_hi:[1,0]
	v_pk_mul_f32 v[138:139], v[138:139], v[176:177] op_sel_hi:[1,0]
	v_mul_f32_e32 v175, 0xbfb8aa3b, v144
	v_pk_mul_f32 v[142:143], v[142:143], v[226:227]
	v_exp_f32_e32 v175, v175
	v_pk_mul_f32 v[138:139], v[138:139], v[142:143]
	v_mul_f32_e32 v142, 0xbfb8aa3b, v145
	v_exp_f32_e32 v143, v142
	v_pk_mul_f32 v[134:135], v[134:135], v[176:177] op_sel_hi:[1,0]
	v_add_f32_e32 v142, 1.0, v175
	v_mul_f32_e32 v175, 0xbfb8aa3b, v134
	v_pk_mul_f32 v[140:141], v[140:141], v[176:177] op_sel_hi:[1,0]
	v_add_f32_e32 v143, 1.0, v143
	v_exp_f32_e32 v175, v175
	v_mul_f32_e32 v177, 0xbfb8aa3b, v135
	v_rcp_f32_e32 v142, v142
	v_exp_f32_e32 v177, v177
	v_rcp_f32_e32 v143, v143
	v_add_f32_e32 v175, 1.0, v175
	v_rcp_f32_e32 v226, v175
	v_add_f32_e32 v175, 1.0, v177
	v_pk_mul_f32 v[142:143], v[144:145], v[142:143]
	v_pk_mul_f32 v[136:137], v[136:137], v[176:177] op_sel_hi:[1,0]
	v_rcp_f32_e32 v227, v175
	v_pk_mul_f32 v[140:141], v[140:141], v[142:143]
	v_mul_f32_e32 v142, 0xbfb8aa3b, v136
	v_mul_f32_e32 v143, 0xbfb8aa3b, v137
	v_exp_f32_e32 v142, v142
	v_exp_f32_e32 v143, v143
	v_pk_mul_f32 v[130:131], v[130:131], v[176:177] op_sel_hi:[1,0]
	v_pk_mul_f32 v[134:135], v[134:135], v[226:227]
	v_pk_mul_f32 v[132:133], v[132:133], v[176:177] op_sel_hi:[1,0]
	v_pk_mul_f32 v[130:131], v[130:131], v[134:135]
	v_add_f32_e32 v134, 1.0, v142
	v_add_f32_e32 v135, 1.0, v143
	v_rcp_f32_e32 v134, v134
	v_rcp_f32_e32 v135, v135
	s_nop 0
	v_pk_mul_f32 v[134:135], v[136:137], v[134:135]
	s_nop 0
	v_pk_mul_f32 v[132:133], v[132:133], v[134:135]
	v_cvt_pk_bf16_f32 v134, v138, v139
	s_waitcnt lgkmcnt(0)
	v_cvt_pk_bf16_f32 v136, v130, v131
	v_cvt_pk_bf16_f32 v137, v132, v133
	v_mov_b64_e32 v[132:133], s[26:27]
	v_cvt_pk_bf16_f32 v135, v140, v141
	s_waitcnt lgkmcnt(0)
	v_mov_b32_e32 v138, v170
	v_mad_i64_i32 v[140:141], s[4:5], v210, s68, v[132:133]
	v_lshlrev_b64 v[130:131], 1, v[224:225]
	v_pk_mul_f32 v[126:127], v[126:127], v[138:139] op_sel_hi:[1,0]
	v_lshl_add_u64 v[140:141], v[140:141], 0, v[130:131]
	v_mul_f32_e32 v139, 0xbfb8aa3b, v126
	v_exp_f32_e32 v139, v139
	global_store_dwordx4 v[140:141], v[134:137], off
	v_pk_mul_f32 v[128:129], v[128:129], v[138:139] op_sel_hi:[1,0]
	s_nop 0
	v_mul_f32_e32 v134, 0xbfb8aa3b, v127
	v_exp_f32_e32 v135, v134
	v_mul_f32_e32 v136, 0xbfb8aa3b, v128
	v_mul_f32_e32 v137, 0xbfb8aa3b, v129
	v_exp_f32_e32 v136, v136
	v_exp_f32_e32 v137, v137
	v_add_f32_e32 v134, 1.0, v139
	v_add_f32_e32 v135, 1.0, v135
	v_rcp_f32_e32 v134, v134
	v_rcp_f32_e32 v135, v135
	v_add_f32_e32 v136, 1.0, v136
	v_add_f32_e32 v137, 1.0, v137
	v_rcp_f32_e32 v136, v136
	v_rcp_f32_e32 v137, v137
	v_pk_mul_f32 v[118:119], v[118:119], v[138:139] op_sel_hi:[1,0]
	v_pk_mul_f32 v[126:127], v[126:127], v[134:135]
	v_pk_mul_f32 v[120:121], v[120:121], v[138:139] op_sel_hi:[1,0]
	v_pk_mul_f32 v[118:119], v[118:119], v[126:127]
	v_pk_mul_f32 v[126:127], v[128:129], v[136:137]
	v_pk_mul_f32 v[122:123], v[122:123], v[138:139] op_sel_hi:[1,0]
	v_pk_mul_f32 v[120:121], v[120:121], v[126:127]
	v_mul_f32_e32 v128, 0xbfb8aa3b, v122
	v_mul_f32_e32 v126, 0xbfb8aa3b, v123
	v_exp_f32_e32 v128, v128
	v_exp_f32_e32 v127, v126
	v_pk_mul_f32 v[124:125], v[124:125], v[138:139] op_sel_hi:[1,0]
	v_pk_mul_f32 v[114:115], v[114:115], v[138:139] op_sel_hi:[1,0]
	v_add_f32_e32 v126, 1.0, v128
	v_add_f32_e32 v127, 1.0, v127
	v_mul_f32_e32 v128, 0xbfb8aa3b, v124
	v_mul_f32_e32 v129, 0xbfb8aa3b, v125
	v_rcp_f32_e32 v126, v126
	v_rcp_f32_e32 v127, v127
	v_exp_f32_e32 v128, v128
	v_exp_f32_e32 v129, v129
	v_pk_mul_f32 v[122:123], v[122:123], v[126:127]
	v_add_f32_e32 v126, 1.0, v128
	v_add_f32_e32 v127, 1.0, v129
	v_rcp_f32_e32 v126, v126
	v_rcp_f32_e32 v127, v127
	v_pk_mul_f32 v[122:123], v[114:115], v[122:123]
	v_pk_mul_f32 v[114:115], v[116:117], v[138:139] op_sel_hi:[1,0]
	v_pk_mul_f32 v[116:117], v[124:125], v[126:127]
	s_waitcnt lgkmcnt(0)
	v_pk_mul_f32 v[124:125], v[114:115], v[116:117]
	v_cvt_pk_bf16_f32 v114, v118, v119
	v_cvt_pk_bf16_f32 v115, v120, v121
	v_mad_i64_i32 v[120:121], s[4:5], v208, s68, v[132:133]
	s_waitcnt lgkmcnt(0)
	v_mov_b32_e32 v118, v166
	v_cvt_pk_bf16_f32 v116, v122, v123
	v_cvt_pk_bf16_f32 v117, v124, v125
	v_lshl_add_u64 v[120:121], v[120:121], 0, v[130:131]
	v_pk_mul_f32 v[110:111], v[110:111], v[118:119] op_sel_hi:[1,0]
	global_store_dwordx4 v[120:121], v[114:117], off
	v_mul_f32_e32 v119, 0xbfb8aa3b, v110
	v_exp_f32_e32 v119, v119
	v_mul_f32_e32 v114, 0xbfb8aa3b, v111
	v_exp_f32_e32 v115, v114
	v_pk_mul_f32 v[112:113], v[112:113], v[118:119] op_sel_hi:[1,0]
	s_nop 0
	v_mul_f32_e32 v116, 0xbfb8aa3b, v112
	v_mul_f32_e32 v117, 0xbfb8aa3b, v113
	v_exp_f32_e32 v116, v116
	v_exp_f32_e32 v117, v117
	v_add_f32_e32 v114, 1.0, v119
	v_add_f32_e32 v115, 1.0, v115
	v_rcp_f32_e32 v114, v114
	v_rcp_f32_e32 v115, v115
	v_add_f32_e32 v116, 1.0, v116
	v_add_f32_e32 v117, 1.0, v117
	v_rcp_f32_e32 v116, v116
	v_rcp_f32_e32 v117, v117
	v_pk_mul_f32 v[98:99], v[98:99], v[118:119] op_sel_hi:[1,0]
	v_pk_mul_f32 v[110:111], v[110:111], v[114:115]
	v_pk_mul_f32 v[100:101], v[100:101], v[118:119] op_sel_hi:[1,0]
	v_pk_mul_f32 v[98:99], v[98:99], v[110:111]
	v_pk_mul_f32 v[110:111], v[112:113], v[116:117]
	v_pk_mul_f32 v[102:103], v[102:103], v[118:119] op_sel_hi:[1,0]
	v_pk_mul_f32 v[100:101], v[100:101], v[110:111]
	v_mul_f32_e32 v112, 0xbfb8aa3b, v102
	v_mul_f32_e32 v110, 0xbfb8aa3b, v103
	v_exp_f32_e32 v112, v112
	v_exp_f32_e32 v111, v110
	v_pk_mul_f32 v[104:105], v[104:105], v[118:119] op_sel_hi:[1,0]
	v_pk_mul_f32 v[94:95], v[94:95], v[118:119] op_sel_hi:[1,0]
	v_add_f32_e32 v110, 1.0, v112
	v_add_f32_e32 v111, 1.0, v111
	v_mul_f32_e32 v112, 0xbfb8aa3b, v104
	v_mul_f32_e32 v113, 0xbfb8aa3b, v105
	v_rcp_f32_e32 v110, v110
	v_rcp_f32_e32 v111, v111
	v_exp_f32_e32 v112, v112
	v_exp_f32_e32 v113, v113
	v_pk_mul_f32 v[102:103], v[102:103], v[110:111]
	v_add_f32_e32 v110, 1.0, v112
	v_add_f32_e32 v111, 1.0, v113
	v_rcp_f32_e32 v110, v110
	v_rcp_f32_e32 v111, v111
	v_pk_mul_f32 v[102:103], v[94:95], v[102:103]
	v_pk_mul_f32 v[94:95], v[96:97], v[118:119] op_sel_hi:[1,0]
	v_pk_mul_f32 v[96:97], v[104:105], v[110:111]
	s_waitcnt lgkmcnt(0)
	v_pk_mul_f32 v[104:105], v[94:95], v[96:97]
	v_cvt_pk_bf16_f32 v94, v98, v99
	v_cvt_pk_bf16_f32 v95, v100, v101
	v_mad_i64_i32 v[100:101], s[4:5], v206, s68, v[132:133]
	s_waitcnt lgkmcnt(0)
	v_mov_b32_e32 v98, v162
	v_cvt_pk_bf16_f32 v96, v102, v103
	v_cvt_pk_bf16_f32 v97, v104, v105
	v_lshl_add_u64 v[100:101], v[100:101], 0, v[130:131]
	v_pk_mul_f32 v[90:91], v[90:91], v[98:99] op_sel_hi:[1,0]
	global_store_dwordx4 v[100:101], v[94:97], off
	v_mul_f32_e32 v99, 0xbfb8aa3b, v90
	v_exp_f32_e32 v99, v99
	v_mul_f32_e32 v94, 0xbfb8aa3b, v91
	v_exp_f32_e32 v95, v94
	v_pk_mul_f32 v[92:93], v[92:93], v[98:99] op_sel_hi:[1,0]
	s_nop 0
	v_mul_f32_e32 v96, 0xbfb8aa3b, v92
	v_mul_f32_e32 v97, 0xbfb8aa3b, v93
	v_exp_f32_e32 v96, v96
	v_exp_f32_e32 v97, v97
	v_add_f32_e32 v94, 1.0, v99
	v_add_f32_e32 v95, 1.0, v95
	v_rcp_f32_e32 v94, v94
	v_rcp_f32_e32 v95, v95
	v_add_f32_e32 v96, 1.0, v96
	v_add_f32_e32 v97, 1.0, v97
	v_rcp_f32_e32 v96, v96
	v_rcp_f32_e32 v97, v97
	v_pk_mul_f32 v[78:79], v[78:79], v[98:99] op_sel_hi:[1,0]
	v_pk_mul_f32 v[90:91], v[90:91], v[94:95]
	v_pk_mul_f32 v[82:83], v[82:83], v[98:99] op_sel_hi:[1,0]
	v_pk_mul_f32 v[78:79], v[78:79], v[90:91]
	v_pk_mul_f32 v[90:91], v[92:93], v[96:97]
	v_mul_f32_e32 v92, 0xbfb8aa3b, v82
	v_exp_f32_e32 v92, v92
	v_pk_mul_f32 v[80:81], v[80:81], v[98:99] op_sel_hi:[1,0]
	v_pk_mul_f32 v[84:85], v[84:85], v[98:99] op_sel_hi:[1,0]
	v_pk_mul_f32 v[80:81], v[80:81], v[90:91]
	v_mul_f32_e32 v90, 0xbfb8aa3b, v83
	v_exp_f32_e32 v91, v90
	v_add_f32_e32 v90, 1.0, v92
	v_mul_f32_e32 v92, 0xbfb8aa3b, v84
	v_mul_f32_e32 v93, 0xbfb8aa3b, v85
	v_exp_f32_e32 v92, v92
	v_exp_f32_e32 v93, v93
	v_add_f32_e32 v91, 1.0, v91
	v_rcp_f32_e32 v90, v90
	v_rcp_f32_e32 v91, v91
	v_add_f32_e32 v92, 1.0, v92
	v_add_f32_e32 v93, 1.0, v93
	v_rcp_f32_e32 v92, v92
	v_rcp_f32_e32 v93, v93
	v_pk_mul_f32 v[74:75], v[74:75], v[98:99] op_sel_hi:[1,0]
	v_pk_mul_f32 v[82:83], v[82:83], v[90:91]
	s_nop 0
	v_pk_mul_f32 v[82:83], v[74:75], v[82:83]
	v_pk_mul_f32 v[74:75], v[76:77], v[98:99] op_sel_hi:[1,0]
	v_pk_mul_f32 v[76:77], v[84:85], v[92:93]
	s_nop 0
	v_pk_mul_f32 v[84:85], v[74:75], v[76:77]
	v_cvt_pk_bf16_f32 v74, v78, v79
	v_mad_i64_i32 v[78:79], s[4:5], v204, s68, v[132:133]
	v_cvt_pk_bf16_f32 v75, v80, v81
	v_cvt_pk_bf16_f32 v76, v82, v83
	v_cvt_pk_bf16_f32 v77, v84, v85
	v_lshl_add_u64 v[78:79], v[78:79], 0, v[130:131]
	global_store_dwordx4 v[78:79], v[74:77], off
	s_andn2_b64 vcc, exec, s[6:7]
	s_cbranch_vccnz .LBB0_1030
	s_waitcnt vmcnt(4)
	global_store_dwordx4 v[248:249], v[146:149], off nt
	global_store_dwordx4 v[250:251], v[154:157], off nt
	global_store_dwordx4 v[252:253], v[150:153], off nt
	global_store_dwordx4 v[254:255], v[158:161], off nt

.LBB0_1035:
	s_or_b64 exec, exec, s[6:7]
	s_nop 0
	s_waitcnt lgkmcnt(0)
	s_waitcnt lgkmcnt(0)
	v_mov_b32_e32 v76, v106
	s_nop 0
	v_pk_mul_f32 v[62:63], v[62:63], v[76:77] op_sel_hi:[1,0]
	v_pk_mul_f32 v[58:59], v[58:59], v[76:77] op_sel_hi:[1,0]
	v_pk_mul_f32 v[64:65], v[64:65], v[76:77] op_sel_hi:[1,0]
	v_pk_mul_f32 v[60:61], v[60:61], v[76:77] op_sel_hi:[1,0]
	v_pk_mul_f32 v[54:55], v[54:55], v[76:77] op_sel_hi:[1,0]
	v_mul_f32_e32 v75, 0xbfb8aa3b, v62
	v_mul_f32_e32 v77, 0xbfb8aa3b, v63
	v_exp_f32_e32 v75, v75
	v_exp_f32_e32 v77, v77
	v_mul_f32_e32 v78, 0xbfb8aa3b, v64
	v_mul_f32_e32 v79, 0xbfb8aa3b, v65
	v_add_f32_e32 v75, 1.0, v75
	v_add_f32_e32 v77, 1.0, v77
	v_exp_f32_e32 v80, v78
	v_exp_f32_e32 v81, v79
	v_rcp_f32_e32 v78, v75
	v_rcp_f32_e32 v79, v77
	v_add_f32_e32 v75, 1.0, v80
	v_add_f32_e32 v77, 1.0, v81
	v_pk_mul_f32 v[56:57], v[56:57], v[76:77] op_sel_hi:[1,0]
	v_pk_mul_f32 v[62:63], v[62:63], v[78:79]
	v_pk_mul_f32 v[50:51], v[50:51], v[76:77] op_sel_hi:[1,0]
	v_pk_mul_f32 v[58:59], v[58:59], v[62:63]
	v_mul_f32_e32 v62, 0xbfb8aa3b, v54
	v_mul_f32_e32 v63, 0xbfb8aa3b, v55
	v_exp_f32_e32 v62, v62
	v_exp_f32_e32 v63, v63
	v_pk_mul_f32 v[52:53], v[52:53], v[76:77] op_sel_hi:[1,0]
	v_rcp_f32_e32 v80, v75
	v_add_f32_e32 v62, 1.0, v62
	v_add_f32_e32 v63, 1.0, v63
	v_rcp_f32_e32 v62, v62
	v_rcp_f32_e32 v63, v63
	v_rcp_f32_e32 v81, v77
	v_pk_mul_f32 v[54:55], v[54:55], v[62:63]
	v_mul_f32_e32 v62, 0xbfb8aa3b, v56
	v_mul_f32_e32 v63, 0xbfb8aa3b, v57
	v_exp_f32_e32 v62, v62
	v_exp_f32_e32 v63, v63
	v_pk_mul_f32 v[50:51], v[50:51], v[54:55]
	v_pk_mul_f32 v[64:65], v[64:65], v[80:81]
	v_add_f32_e32 v54, 1.0, v62
	v_add_f32_e32 v55, 1.0, v63
	v_rcp_f32_e32 v54, v54
	v_rcp_f32_e32 v55, v55
	v_pk_mul_f32 v[60:61], v[60:61], v[64:65]
	v_pk_mul_f32 v[54:55], v[56:57], v[54:55]
	s_nop 0
	v_pk_mul_f32 v[56:57], v[52:53], v[54:55]
	v_cvt_pk_bf16_f32 v52, v58, v59
	s_waitcnt lgkmcnt(0)
	v_cvt_pk_bf16_f32 v55, v56, v57
	v_cvt_pk_bf16_f32 v54, v50, v51
	v_mov_b64_e32 v[50:51], s[26:27]
	v_cvt_pk_bf16_f32 v53, v60, v61
	s_waitcnt lgkmcnt(0)
	v_mov_b32_e32 v56, v86
	v_mad_i64_i32 v[58:59], s[0:1], v202, s68, v[50:51]
	v_lshl_add_u64 v[58:59], v[58:59], 0, v[130:131]
	v_pk_mul_f32 v[46:47], v[46:47], v[56:57] op_sel_hi:[1,0]
	global_store_dwordx4 v[58:59], v[52:55], off
	v_mul_f32_e32 v57, 0xbfb8aa3b, v46
	v_exp_f32_e32 v57, v57
	v_mul_f32_e32 v52, 0xbfb8aa3b, v47
	v_exp_f32_e32 v53, v52
	v_pk_mul_f32 v[48:49], v[48:49], v[56:57] op_sel_hi:[1,0]
	s_nop 0
	v_mul_f32_e32 v54, 0xbfb8aa3b, v48
	v_mul_f32_e32 v55, 0xbfb8aa3b, v49
	v_exp_f32_e32 v54, v54
	v_exp_f32_e32 v55, v55
	v_add_f32_e32 v52, 1.0, v57
	v_add_f32_e32 v53, 1.0, v53
	v_rcp_f32_e32 v52, v52
	v_rcp_f32_e32 v53, v53
	v_add_f32_e32 v54, 1.0, v54
	v_add_f32_e32 v55, 1.0, v55
	v_rcp_f32_e32 v54, v54
	v_rcp_f32_e32 v55, v55
	v_pk_mul_f32 v[38:39], v[38:39], v[56:57] op_sel_hi:[1,0]
	v_pk_mul_f32 v[46:47], v[46:47], v[52:53]
	v_pk_mul_f32 v[40:41], v[40:41], v[56:57] op_sel_hi:[1,0]
	v_pk_mul_f32 v[38:39], v[38:39], v[46:47]
	v_pk_mul_f32 v[46:47], v[48:49], v[54:55]
	v_pk_mul_f32 v[42:43], v[42:43], v[56:57] op_sel_hi:[1,0]
	v_pk_mul_f32 v[40:41], v[40:41], v[46:47]
	v_mul_f32_e32 v48, 0xbfb8aa3b, v42
	v_mul_f32_e32 v46, 0xbfb8aa3b, v43
	v_exp_f32_e32 v48, v48
	v_exp_f32_e32 v47, v46
	v_pk_mul_f32 v[44:45], v[44:45], v[56:57] op_sel_hi:[1,0]
	v_pk_mul_f32 v[34:35], v[34:35], v[56:57] op_sel_hi:[1,0]
	v_add_f32_e32 v46, 1.0, v48
	v_add_f32_e32 v47, 1.0, v47
	v_mul_f32_e32 v48, 0xbfb8aa3b, v44
	v_mul_f32_e32 v49, 0xbfb8aa3b, v45
	v_rcp_f32_e32 v46, v46
	v_rcp_f32_e32 v47, v47
	v_exp_f32_e32 v48, v48
	v_exp_f32_e32 v49, v49
	v_pk_mul_f32 v[42:43], v[42:43], v[46:47]
	v_add_f32_e32 v46, 1.0, v48
	v_add_f32_e32 v47, 1.0, v49
	v_rcp_f32_e32 v46, v46
	v_rcp_f32_e32 v47, v47
	v_pk_mul_f32 v[42:43], v[34:35], v[42:43]
	v_pk_mul_f32 v[34:35], v[36:37], v[56:57] op_sel_hi:[1,0]
	v_pk_mul_f32 v[36:37], v[44:45], v[46:47]
	s_waitcnt lgkmcnt(0)
	v_pk_mul_f32 v[44:45], v[34:35], v[36:37]
	v_cvt_pk_bf16_f32 v34, v38, v39
	v_cvt_pk_bf16_f32 v35, v40, v41
	v_mad_i64_i32 v[40:41], s[0:1], v200, s68, v[50:51]
	s_waitcnt lgkmcnt(0)
	v_mov_b32_e32 v38, v70
	v_cvt_pk_bf16_f32 v36, v42, v43
	v_cvt_pk_bf16_f32 v37, v44, v45
	v_lshl_add_u64 v[40:41], v[40:41], 0, v[130:131]
	v_pk_mul_f32 v[30:31], v[30:31], v[38:39] op_sel_hi:[1,0]
	global_store_dwordx4 v[40:41], v[34:37], off
	v_mul_f32_e32 v39, 0xbfb8aa3b, v30
	v_exp_f32_e32 v39, v39
	v_mul_f32_e32 v34, 0xbfb8aa3b, v31
	v_exp_f32_e32 v35, v34
	v_pk_mul_f32 v[32:33], v[32:33], v[38:39] op_sel_hi:[1,0]
	s_nop 0
	v_mul_f32_e32 v36, 0xbfb8aa3b, v32
	v_mul_f32_e32 v37, 0xbfb8aa3b, v33
	v_exp_f32_e32 v36, v36
	v_exp_f32_e32 v37, v37
	v_add_f32_e32 v34, 1.0, v39
	v_add_f32_e32 v35, 1.0, v35
	v_rcp_f32_e32 v34, v34
	v_rcp_f32_e32 v35, v35
	v_add_f32_e32 v36, 1.0, v36
	v_add_f32_e32 v37, 1.0, v37
	v_rcp_f32_e32 v36, v36
	v_rcp_f32_e32 v37, v37
	v_pk_mul_f32 v[22:23], v[22:23], v[38:39] op_sel_hi:[1,0]
	v_pk_mul_f32 v[30:31], v[30:31], v[34:35]
	v_pk_mul_f32 v[24:25], v[24:25], v[38:39] op_sel_hi:[1,0]
	v_pk_mul_f32 v[22:23], v[22:23], v[30:31]
	v_pk_mul_f32 v[30:31], v[32:33], v[36:37]
	v_pk_mul_f32 v[26:27], v[26:27], v[38:39] op_sel_hi:[1,0]
	v_pk_mul_f32 v[24:25], v[24:25], v[30:31]
	v_mul_f32_e32 v32, 0xbfb8aa3b, v26
	v_mul_f32_e32 v30, 0xbfb8aa3b, v27
	v_exp_f32_e32 v32, v32
	v_exp_f32_e32 v31, v30
	v_pk_mul_f32 v[28:29], v[28:29], v[38:39] op_sel_hi:[1,0]
	v_pk_mul_f32 v[18:19], v[18:19], v[38:39] op_sel_hi:[1,0]
	v_add_f32_e32 v30, 1.0, v32
	v_add_f32_e32 v31, 1.0, v31
	v_mul_f32_e32 v32, 0xbfb8aa3b, v28
	v_mul_f32_e32 v33, 0xbfb8aa3b, v29
	v_rcp_f32_e32 v30, v30
	v_rcp_f32_e32 v31, v31
	v_exp_f32_e32 v32, v32
	v_exp_f32_e32 v33, v33
	v_pk_mul_f32 v[26:27], v[26:27], v[30:31]
	v_add_f32_e32 v30, 1.0, v32
	v_add_f32_e32 v31, 1.0, v33
	v_rcp_f32_e32 v30, v30
	v_rcp_f32_e32 v31, v31
	v_pk_mul_f32 v[26:27], v[18:19], v[26:27]
	v_pk_mul_f32 v[18:19], v[20:21], v[38:39] op_sel_hi:[1,0]
	v_pk_mul_f32 v[20:21], v[28:29], v[30:31]
	s_waitcnt lgkmcnt(0)
	v_pk_mul_f32 v[28:29], v[18:19], v[20:21]
	v_cvt_pk_bf16_f32 v18, v22, v23
	v_cvt_pk_bf16_f32 v19, v24, v25
	v_mad_i64_i32 v[24:25], s[0:1], v198, s68, v[50:51]
	s_waitcnt lgkmcnt(0)
	v_mov_b32_e32 v22, v66
	v_cvt_pk_bf16_f32 v20, v26, v27
	v_cvt_pk_bf16_f32 v21, v28, v29
	v_lshl_add_u64 v[24:25], v[24:25], 0, v[130:131]
	v_pk_mul_f32 v[14:15], v[14:15], v[22:23] op_sel_hi:[1,0]
	global_store_dwordx4 v[24:25], v[18:21], off
	v_mul_f32_e32 v23, 0xbfb8aa3b, v14
	v_exp_f32_e32 v23, v23
	v_mul_f32_e32 v18, 0xbfb8aa3b, v15
	v_exp_f32_e32 v19, v18
	v_pk_mul_f32 v[16:17], v[16:17], v[22:23] op_sel_hi:[1,0]
	s_nop 0
	v_mul_f32_e32 v20, 0xbfb8aa3b, v16
	v_mul_f32_e32 v21, 0xbfb8aa3b, v17
	v_exp_f32_e32 v20, v20
	v_exp_f32_e32 v21, v21
	v_add_f32_e32 v18, 1.0, v23
	v_add_f32_e32 v19, 1.0, v19
	v_rcp_f32_e32 v18, v18
	v_rcp_f32_e32 v19, v19
	v_add_f32_e32 v20, 1.0, v20
	v_add_f32_e32 v21, 1.0, v21
	v_rcp_f32_e32 v20, v20
	v_rcp_f32_e32 v21, v21
	v_pk_mul_f32 v[6:7], v[6:7], v[22:23] op_sel_hi:[1,0]
	v_pk_mul_f32 v[14:15], v[14:15], v[18:19]
	v_pk_mul_f32 v[10:11], v[10:11], v[22:23] op_sel_hi:[1,0]
	v_pk_mul_f32 v[6:7], v[6:7], v[14:15]
	v_pk_mul_f32 v[14:15], v[16:17], v[20:21]
	v_mul_f32_e32 v16, 0xbfb8aa3b, v10
	v_exp_f32_e32 v16, v16
	v_pk_mul_f32 v[8:9], v[8:9], v[22:23] op_sel_hi:[1,0]
	v_pk_mul_f32 v[12:13], v[12:13], v[22:23] op_sel_hi:[1,0]
	v_pk_mul_f32 v[8:9], v[8:9], v[14:15]
	v_mul_f32_e32 v14, 0xbfb8aa3b, v11
	v_exp_f32_e32 v15, v14
	v_add_f32_e32 v14, 1.0, v16
	v_mul_f32_e32 v16, 0xbfb8aa3b, v12
	v_mul_f32_e32 v17, 0xbfb8aa3b, v13
	v_exp_f32_e32 v16, v16
	v_exp_f32_e32 v17, v17
	v_add_f32_e32 v15, 1.0, v15
	v_rcp_f32_e32 v14, v14
	v_rcp_f32_e32 v15, v15
	v_add_f32_e32 v16, 1.0, v16
	v_add_f32_e32 v17, 1.0, v17
	v_rcp_f32_e32 v16, v16
	v_rcp_f32_e32 v17, v17
	v_pk_mul_f32 v[2:3], v[2:3], v[22:23] op_sel_hi:[1,0]
	v_pk_mul_f32 v[10:11], v[10:11], v[14:15]
	s_nop 0
	v_pk_mul_f32 v[10:11], v[2:3], v[10:11]
	v_pk_mul_f32 v[2:3], v[4:5], v[22:23] op_sel_hi:[1,0]
	v_pk_mul_f32 v[4:5], v[12:13], v[16:17]
	s_nop 0
	v_pk_mul_f32 v[12:13], v[2:3], v[4:5]
	v_cvt_pk_bf16_f32 v2, v6, v7
	v_mad_i64_i32 v[6:7], s[0:1], v196, s68, v[50:51]
	v_cvt_pk_bf16_f32 v3, v8, v9
	v_cvt_pk_bf16_f32 v4, v10, v11
	v_cvt_pk_bf16_f32 v5, v12, v13
	v_lshl_add_u64 v[6:7], v[6:7], 0, v[130:131]
	global_store_dwordx4 v[6:7], v[2:5], off
	s_and_saveexec_b64 s[6:7], s[80:81]
	s_cbranch_execz .LBB0_1037
	s_cmp_eq_u32 s98, 0
	s_cbranch_scc1 .Ls4dr_no
	s_waitcnt vmcnt(4)
	v_readfirstlane_b32 s0, v247
	s_nop 1
	v_add_u32_e32 v74, s0, v74
	v_min_u32_e32 v74, 0x8b7, v74
	v_add_u32_e32 v74, 0xc99, v74
